# weight copies refreshed in the P1->P2 barrier and touched in the P2->P3 barrier; w_down / w_ple_gate / E_raw / sample-chain scratch touched in the hand-off waits
# speedup vs baseline: 1.0148x; 1.0148x over previous
.LBB0_290:
	v_readlane_b32 s72, v251, 2
	v_readlane_b32 s73, v251, 3
	s_cmp_lt_i32 s73, 3
	v_readlane_b32 s56, v250, 3
	v_readlane_b32 s74, v251, 4
	v_readlane_b32 s75, v251, 5
	s_cbranch_scc1 .LBB0_344
	s_waitcnt vmcnt(0)
	s_barrier
	v_readfirstlane_b32 s1, v0
	s_cmp_lt_u32 s1, 64
	s_cbranch_scc1 .Lmy_touchw2_skip
	v_readlane_b32 s98, v251, 20
	v_readlane_b32 s99, v251, 21
	s_mul_i32 s0, s70, 0x14000
	s_add_u32 s0, s0, 0x800000
	s_add_u32 s98, s98, s0
	s_addc_u32 s99, s99, 0
	v_add_u32_e32 v252, 0xffffffc0, v0
	v_lshlrev_b32_e32 v252, 6, v252
	s_nop 1
	global_load_dword v255, v252, s[98:99]
	v_add_u32_e32 v253, 0x7000, v252
	global_load_dword v255, v253, s[98:99]
	v_add_u32_e32 v253, 0xe000, v252
	global_load_dword v255, v253, s[98:99]

.Lmy_touchw_skip:
	v_readfirstlane_b32 s1, v0
	s_cmp_lt_u32 s1, 64
	s_cbranch_scc1 .Lmy_touchxs_skip
	s_lshl_b32 s0, s70, 11
	s_add_u32 s98, s78, s0
	s_addc_u32 s99, s79, 0
	v_and_b32_e32 v252, 31, v0
	v_lshlrev_b32_e32 v252, 6, v252
	s_nop 1
	global_load_dword v255, v252, s[98:99]

.Lmy_t6_skip:
	v_readfirstlane_b32 s98, v0
	s_cmp_lt_u32 s98, 256
	s_cbranch_scc1 .Lmy_t6b_skip
	v_readlane_b32 s98, v251, 20
	v_readlane_b32 s99, v251, 21
	s_lshl_b32 s100, s70, 11
	s_add_u32 s100, s100, 0x3100000
	s_add_u32 s100, s98, s100
	s_addc_u32 s101, s99, 0
	v_and_b32_e32 v252, 31, v0
	v_lshlrev_b32_e32 v252, 6, v252
	s_nop 1
	global_load_dword v255, v252, s[100:101]
	s_add_u32 s100, s98, 0x3400000
	s_addc_u32 s101, s99, 0
	v_and_b32_e32 v252, 0x7f, v0
	v_lshlrev_b32_e32 v252, 6, v252
	s_nop 1
	global_load_dword v255, v252, s[100:101]
	v_readlane_b32 s100, v251, 16
	v_readlane_b32 s101, v251, 17
	v_and_b32_e32 v252, 63, v0
	v_lshlrev_b32_e32 v252, 6, v252
	s_nop 3
	global_load_dword v255, v252, s[100:101]
